# row sum-of-squares lane reductions (xor 16, xor 32) in the residual-GEMM and FFN-in epilogues: ds_bpermute round trips replaced by v_permlane16_swap / v_permlane32_swap (32 sites)
# speedup vs baseline: 1.0133x; 1.0002x over previous
;     __device__ __forceinline__ void operator()(f32x4 (&acc)[2][2][4][2], const Unit& u, int wr, int wc, int fr, int fq) const {
;         const int lane = fq * 16 + fr;
;         const int rowt = u.pm * 254;
; #pragma unroll
;         for (int ai = 0; ai < 2; ++ai)
; #pragma unroll
;             for (int m = 0; m < 4; ++m) { const int row = rowt + ai * 128 + wr * 64 + m * 16 + fr; const f32x4 pv = *(const f32x4*)(ssq + (size_t)row * 16 + 4 * fq); float sq = (pv[0] + pv[1]) + (pv[2] + pv[3]); sq += __shfl_xor(sq, 16); sq += __shfl_xor(sq, 32);
;                 const float rs = rsqrtf(sq * (1.0f / 1024.0f) + NEPS);
; #pragma unroll
;                 for (int bj = 0; bj < 2; ++bj)
; #pragma unroll
;                     for (int n = 0; n < 2; ++n) acc[ai][bj][m][n] = acc[ai][bj][m][n] * rs;
.LBB0_416:
	v_and_b32_e32 v190, 64, v198
	v_xor_b32_e32 v130, 16, v198
	v_add_u32_e32 v131, 64, v190
	v_cmp_lt_i32_e32 vcc, v130, v131
	s_mulk_i32 s2, 0xfe
	v_add_u32_e32 v170, s2, v205
	v_cndmask_b32_e32 v130, v198, v130, vcc
	v_lshlrev_b32_e32 v147, 2, v130
	v_xor_b32_e32 v130, 32, v198
	v_cmp_lt_i32_e32 vcc, v130, v131
	v_ashrrev_i32_e32 v171, 31, v170
	s_mov_b32 s12, 0x3a800000
	v_cndmask_b32_e32 v130, v198, v130, vcc
	v_lshlrev_b32_e32 v146, 2, v130
	s_mov_b32 s24, s97
	s_mov_b32 s15, s96
	v_cmp_lt_i32_e64 s[72:73], 14, v204
	v_lshlrev_b64 v[130:131], 6, v[170:171]
	v_lshl_add_u64 v[130:131], v[154:155], 0, v[130:131]
	global_load_dwordx4 v[130:133], v[130:131], off
	v_add_u32_e32 v134, 0x10, v170
	v_ashrrev_i32_e32 v135, 31, v134
	v_lshlrev_b64 v[134:135], 6, v[134:135]
	v_lshl_add_u64 v[134:135], v[154:155], 0, v[134:135]
	global_load_dwordx4 v[134:137], v[134:135], off
	v_add_u32_e32 v138, 0x20, v170
	v_ashrrev_i32_e32 v139, 31, v138
	v_lshlrev_b64 v[138:139], 6, v[138:139]
	v_lshl_add_u64 v[138:139], v[154:155], 0, v[138:139]
	global_load_dwordx4 v[138:141], v[138:139], off
	v_add_u32_e32 v142, 0x30, v170
	v_ashrrev_i32_e32 v143, 31, v142
	v_lshlrev_b64 v[142:143], 6, v[142:143]
	v_lshl_add_u64 v[142:143], v[154:155], 0, v[142:143]
	global_load_dwordx4 v[142:145], v[142:143], off
	v_add_u32_e32 v160, 0x80, v170
	v_ashrrev_i32_e32 v161, 31, v160
	v_lshlrev_b64 v[160:161], 6, v[160:161]
	v_lshl_add_u64 v[160:161], v[154:155], 0, v[160:161]
	global_load_dwordx4 v[160:163], v[160:161], off
	v_add_u32_e32 v172, 0x90, v170
	v_ashrrev_i32_e32 v173, 31, v172
	v_lshlrev_b64 v[172:173], 6, v[172:173]
	v_lshl_add_u64 v[172:173], v[154:155], 0, v[172:173]
	global_load_dwordx4 v[172:175], v[172:173], off
	v_add_u32_e32 v184, 0xa0, v170
	v_ashrrev_i32_e32 v185, 31, v184
	v_lshlrev_b64 v[184:185], 6, v[184:185]
	v_lshl_add_u64 v[184:185], v[154:155], 0, v[184:185]
	global_load_dwordx4 v[184:187], v[184:185], off
	s_waitcnt vmcnt(6)
	v_add_f32_e32 v130, v131, v130
	v_add_f32_e32 v132, v132, v133
	v_add_f32_e32 v200, v130, v132
	v_add_u32_e32 v130, 0xb0, v170
	v_ashrrev_i32_e32 v131, 31, v130
	v_lshlrev_b64 v[130:131], 6, v[130:131]
	v_lshl_add_u64 v[130:131], v[154:155], 0, v[130:131]
	global_load_dwordx4 v[130:133], v[130:131], off
	s_waitcnt vmcnt(6)
	v_add_f32_e32 v134, v135, v134
	v_add_f32_e32 v136, v136, v137
	v_add_f32_e32 v134, v134, v136
	s_waitcnt vmcnt(5)
	v_add_f32_e32 v138, v139, v138
	v_add_f32_e32 v140, v140, v141
	v_add_f32_e32 v138, v138, v140
	s_waitcnt vmcnt(4)
	v_add_f32_e32 v142, v143, v142
	v_add_f32_e32 v144, v144, v145
	v_add_f32_e32 v142, v142, v144
	s_waitcnt vmcnt(3)
	v_add_f32_e32 v160, v161, v160
	v_add_f32_e32 v162, v162, v163
	v_add_f32_e32 v160, v160, v162
	s_waitcnt vmcnt(2)
	v_add_f32_e32 v172, v173, v172
	v_add_f32_e32 v174, v174, v175
	v_add_f32_e32 v172, v172, v174
	s_waitcnt vmcnt(1)
	v_add_f32_e32 v184, v185, v184
	v_add_f32_e32 v186, v186, v187
	v_add_f32_e32 v184, v184, v186
	s_waitcnt vmcnt(0)
	v_add_f32_e32 v130, v131, v130
	v_add_f32_e32 v132, v132, v133
	v_add_f32_e32 v130, v130, v132
	v_mov_b32_e32 v201, v200
	s_nop 1
	v_permlane16_swap_b32_e32 v201, v200
	s_nop 1
	v_mov_b32_e32 v135, v134
	s_nop 1
	v_permlane16_swap_b32_e32 v135, v134
	s_nop 1
	v_mov_b32_e32 v139, v138
	s_nop 1
	v_permlane16_swap_b32_e32 v139, v138
	s_nop 1
	v_mov_b32_e32 v143, v142
	s_nop 1
	v_permlane16_swap_b32_e32 v143, v142
	s_nop 1
	v_mov_b32_e32 v161, v160
	s_nop 1
	v_permlane16_swap_b32_e32 v161, v160
	s_nop 1
	v_mov_b32_e32 v173, v172
	s_nop 1
	v_permlane16_swap_b32_e32 v173, v172
	s_nop 1
	v_mov_b32_e32 v185, v184
	s_nop 1
	v_permlane16_swap_b32_e32 v185, v184
	s_nop 1
	v_mov_b32_e32 v131, v130
	s_nop 1
	v_permlane16_swap_b32_e32 v131, v130
	s_nop 1
	s_waitcnt lgkmcnt(0)
	v_add_f32_e32 v200, v200, v201
	v_add_f32_e32 v134, v134, v135
	v_add_f32_e32 v138, v138, v139
	v_add_f32_e32 v142, v142, v143
	v_add_f32_e32 v160, v160, v161
	v_add_f32_e32 v172, v172, v173
	v_add_f32_e32 v184, v184, v185
	v_add_f32_e32 v130, v130, v131
	v_mov_b32_e32 v201, v200
	s_nop 1
	v_permlane32_swap_b32_e32 v201, v200
	s_nop 1
	v_mov_b32_e32 v135, v134
	s_nop 1
	v_permlane32_swap_b32_e32 v135, v134
	s_nop 1
	v_mov_b32_e32 v139, v138
	s_nop 1
	v_permlane32_swap_b32_e32 v139, v138
	s_nop 1
	v_mov_b32_e32 v143, v142
	s_nop 1
	v_permlane32_swap_b32_e32 v143, v142
	s_nop 1
	v_mov_b32_e32 v161, v160
	s_nop 1
	v_permlane32_swap_b32_e32 v161, v160
	s_nop 1
	v_mov_b32_e32 v173, v172
	s_nop 1
	v_permlane32_swap_b32_e32 v173, v172
	s_nop 1
	v_mov_b32_e32 v185, v184
	s_nop 1
	v_permlane32_swap_b32_e32 v185, v184
	s_nop 1
	v_mov_b32_e32 v131, v130
	s_nop 1
	v_permlane32_swap_b32_e32 v131, v130
	s_nop 1
	s_waitcnt lgkmcnt(0)
	v_add_f32_e32 v200, v200, v201
	v_add_f32_e32 v134, v134, v135
	v_add_f32_e32 v138, v138, v139
	v_add_f32_e32 v142, v142, v143
	v_add_f32_e32 v160, v160, v161
	v_add_f32_e32 v172, v172, v173
	v_add_f32_e32 v184, v184, v185
	v_add_f32_e32 v130, v130, v131
	v_fma_f32 v175, v184, s12, v196
	v_fma_f32 v184, v134, s12, v196
	v_fma_f32 v185, v200, s12, v196
	v_fma_f32 v187, v138, s12, v196
	v_fma_f32 v186, v142, s12, v196
	v_fma_f32 v173, v160, s12, v196
	v_fma_f32 v172, v172, s12, v196
	v_fma_f32 v174, v130, s12, v196
	v_cmp_gt_f32_e32 vcc, s33, v184
	v_cmp_gt_f32_e64 s[68:69], s33, v185
	v_cmp_gt_f32_e64 s[62:63], s33, v187
	v_cmp_gt_f32_e64 s[70:71], s33, v186
	v_cmp_gt_f32_e64 s[58:59], s33, v172
	v_cmp_gt_f32_e64 s[64:65], s33, v173
	s_mov_b64 s[12:13], 0
	v_cmp_gt_f32_e64 s[60:61], s33, v175
	v_cmp_gt_f32_e64 s[66:67], s33, v174
	s_and_saveexec_b64 s[94:95], s[72:73]
	s_xor_b64 s[72:73], exec, s[94:95]
	s_mov_b64 s[12:13], exec
	s_or_saveexec_b64 s[72:73], s[72:73]
	v_mul_f32_e32 v130, 0x4b800000, v185
	v_cndmask_b32_e64 v130, v185, v130, s[68:69]
	v_rsq_f32_e32 v130, v130
	v_mul_f32_e32 v131, 0x4b800000, v186
	v_cndmask_b32_e64 v131, v186, v131, s[70:71]
	v_rsq_f32_e32 v131, v131
	v_mul_f32_e32 v132, 0x45800000, v130
	v_cndmask_b32_e64 v182, v130, v132, s[68:69]
	v_pk_mul_f32 v[142:143], v[126:127], v[182:183] op_sel_hi:[1,0]
	v_mul_f32_e32 v126, 0x45800000, v131
	v_cndmask_b32_e64 v176, v131, v126, s[70:71]
	v_pk_mul_f32 v[120:121], v[120:121], v[176:177] op_sel_hi:[1,0]
	v_pk_mul_f32 v[116:117], v[116:117], v[176:177] op_sel_hi:[1,0]
	v_pk_mul_f32 v[144:145], v[128:129], v[182:183] op_sel_hi:[1,0]
	v_pk_mul_f32 v[118:119], v[118:119], v[176:177] op_sel_hi:[1,0]
	v_pk_mul_f32 v[114:115], v[114:115], v[176:177] op_sel_hi:[1,0]
	v_readlane_b32 s68, v254, 35
	v_mov_b64_e32 v[128:129], v[116:117]
	v_mov_b64_e32 v[132:133], v[120:121]
	v_pk_mul_f32 v[124:125], v[124:125], v[182:183] op_sel_hi:[1,0]
	v_pk_mul_f32 v[122:123], v[122:123], v[182:183] op_sel_hi:[1,0]
	v_mov_b32_e32 v134, s68
	v_mov_b64_e32 v[126:127], v[114:115]
	v_mov_b64_e32 v[130:131], v[118:119]
	s_xor_b64 exec, exec, s[72:73]
	s_cbranch_execz .LBB0_420
; #define PG8_LAS __attribute__((address_space(3)))
;     __device__ __forceinline__ void operator()(f32x4 (&acc)[2][2][4][2], const Unit& u, int wr, int wc, int fr, int fq) const {
;     ...
;                     for (int n = 0; n < 2; ++n) acc[ai][bj][m][n] = acc[ai][bj][m][n] * rs;
;                 asm volatile("" ::: "memory"); }
;         const int colw = wc * 32 + 8 * fq;
;         PG8_LAS float* edgeF = edge; PG8_LAS float* edgeL = edge + 512;
; #pragma unroll
;         for (int ai = 0; ai < 2; ++ai) { const int blk = 2 * ai + wr;
;             if (fr == 0) {
; #pragma unroll
;                 for (int n = 0; n < 2; ++n)
; #pragma unroll
;                     for (int e = 0; e < 4; ++e) edgeF[blk * 128 + colw + 4 * n + e] = acc[ai][0][0][n][e]; }
;             if (fr == 15) {
; #pragma unroll
;                 for (int n = 0; n < 2; ++n)
; #pragma unroll
;                     for (int e = 0; e < 4; ++e) edgeL[blk * 128 + colw + 4 * n + e] = acc[ai][0][3][n][e]; } }
	v_readlane_b32 s68, v254, 36
	s_andn2_b64 s[12:13], s[12:13], exec
	v_mov_b64_e32 v[128:129], v[124:125]
	v_mov_b32_e32 v134, s68
	s_and_b64 s[68:69], s[36:37], exec
	v_mov_b64_e32 v[130:131], v[142:143]
	s_or_b64 s[12:13], s[12:13], s[68:69]
	v_mov_b64_e32 v[126:127], v[122:123]
	v_mov_b64_e32 v[132:133], v[144:145]

; __device__ __forceinline__ u32x4 pack8(const f32x4 a, const f32x4 b) { u32x4 w; w.x = cvt_pk_bf16(a[0], a[1]); w.y = cvt_pk_bf16(a[2], a[3]); w.z = cvt_pk_bf16(b[0], b[1]); w.w = cvt_pk_bf16(b[2], b[3]); return w; }
;     __device__ __forceinline__ void operator()(const f32x4 (&acc)[2][2][4][2], const Unit& u, int wr, int wc, int fr, int fq) const {
;     ...
;                 for (int bj = 0; bj < 2; ++bj) { const size_t off = (size_t)row * 1024 + col0 + bj * 128; const u32x4 hv = __builtin_nontemporal_load((const u32x4*)(hin + off));
;                     f32x4 v0 = acc[ai][bj][m][0], v1 = acc[ai][bj][m][1];
;                     v0[0] += __uint_as_float(hv.x << 16); v0[1] += __uint_as_float(hv.x & 0xffff0000u); v0[2] += __uint_as_float(hv.y << 16); v0[3] += __uint_as_float(hv.y & 0xffff0000u);
;                     v1[0] += __uint_as_float(hv.z << 16); v1[1] += __uint_as_float(hv.z & 0xffff0000u); v1[2] += __uint_as_float(hv.w << 16); v1[3] += __uint_as_float(hv.w & 0xffff0000u);
; #pragma unroll
;                     for (int e = 0; e < 4; ++e) s += v0[e] * v0[e] + v1[e] * v1[e];
;                     if (!pad) *(u32x4*)(hout + off) = pack8(v0, v1); }
;                 s += __shfl_xor(s, 16); s += __shfl_xor(s, 32);
;                 if (fq == 0) ssq[(size_t)row * 16 + u.pn * 4 + wc] = pad ? 0.f : s;
.LBB0_558:
	s_or_b64 exec, exec, s[52:53]
	v_pk_mul_f32 v[122:123], v[122:123], v[122:123]
	v_pk_mul_f32 v[124:125], v[124:125], v[124:125]
	v_pk_fma_f32 v[122:123], v[126:127], v[126:127], v[122:123]
	v_pk_mul_f32 v[114:115], v[114:115], v[114:115]
	v_pk_fma_f32 v[124:125], v[128:129], v[128:129], v[124:125]
	v_pk_fma_f32 v[114:115], v[118:119], v[118:119], v[114:115]
	v_add_f32_e32 v118, v122, v123
	v_add_f32_e32 v118, v124, v118
	v_add_f32_e32 v118, v125, v118
	v_pk_mul_f32 v[116:117], v[116:117], v[116:117]
	v_add_f32_e32 v114, v118, v114
	v_pk_fma_f32 v[116:117], v[120:121], v[120:121], v[116:117]
	v_add_f32_e32 v114, v115, v114
	v_add_f32_e32 v114, v116, v114
	v_and_b32_e32 v116, 64, v198
	v_xor_b32_e32 v115, 16, v198
	v_add_u32_e32 v116, 64, v116
	v_cmp_lt_i32_e32 vcc, v115, v116
	v_add_f32_e32 v114, v117, v114
	v_xor_b32_e32 v117, 32, v198
	v_cndmask_b32_e32 v115, v198, v115, vcc
	v_lshlrev_b32_e32 v120, 2, v115
	v_mov_b32_e32 v115, v114
	s_nop 1
	v_permlane16_swap_b32_e32 v115, v114
	s_nop 1
	v_cmp_lt_i32_e32 vcc, v117, v116
	s_lshl_b32 s52, s24, 2
	s_ashr_i32 s53, s52, 31
	v_cndmask_b32_e32 v116, v198, v117, vcc
	v_lshlrev_b32_e32 v121, 2, v116
	s_waitcnt lgkmcnt(0)
	v_add_f32_e32 v114, v114, v115
	v_mov_b32_e32 v115, v114
	s_nop 1
	v_permlane32_swap_b32_e32 v115, v114
	s_nop 1
	s_and_saveexec_b64 s[12:13], s[36:37]
	s_cbranch_execz .LBB0_560
	v_lshlrev_b64 v[116:117], 6, v[142:143]
	v_lshl_add_u64 v[116:117], s[10:11], 0, v[116:117]
	v_lshl_add_u64 v[116:117], s[52:53], 2, v[116:117]
	s_lshl_b32 s24, s68, 2
	s_waitcnt lgkmcnt(0)
	v_add_f32_e32 v114, v114, v115
	v_lshl_add_u64 v[116:117], v[116:117], 0, s[24:25]
	v_cndmask_b32_e64 v114, v114, 0, s[54:55]
	global_store_dword v[116:117], v114, off

; __device__ __forceinline__ u32x4 pack8(const f32x4 a, const f32x4 b) { u32x4 w; w.x = cvt_pk_bf16(a[0], a[1]); w.y = cvt_pk_bf16(a[2], a[3]); w.z = cvt_pk_bf16(b[0], b[1]); w.w = cvt_pk_bf16(b[2], b[3]); return w; }
;     __device__ __forceinline__ void operator()(const f32x4 (&acc)[2][2][4][2], const Unit& u, int wr, int wc, int fr, int fq) const {
;     ...
;                 for (int bj = 0; bj < 2; ++bj) { const size_t off = (size_t)row * 1024 + col0 + bj * 128; const u32x4 hv = __builtin_nontemporal_load((const u32x4*)(hin + off));
;                     f32x4 v0 = acc[ai][bj][m][0], v1 = acc[ai][bj][m][1];
;                     v0[0] += __uint_as_float(hv.x << 16); v0[1] += __uint_as_float(hv.x & 0xffff0000u); v0[2] += __uint_as_float(hv.y << 16); v0[3] += __uint_as_float(hv.y & 0xffff0000u);
;                     v1[0] += __uint_as_float(hv.z << 16); v1[1] += __uint_as_float(hv.z & 0xffff0000u); v1[2] += __uint_as_float(hv.w << 16); v1[3] += __uint_as_float(hv.w & 0xffff0000u);
; #pragma unroll
;                     for (int e = 0; e < 4; ++e) s += v0[e] * v0[e] + v1[e] * v1[e];
;                     if (!pad) *(u32x4*)(hout + off) = pack8(v0, v1); }
;                 s += __shfl_xor(s, 16); s += __shfl_xor(s, 32);
;                 if (fq == 0) ssq[(size_t)row * 16 + u.pn * 4 + wc] = pad ? 0.f : s;
.LBB0_572:
	s_or_b64 exec, exec, s[56:57]
	v_pk_mul_f32 v[106:107], v[106:107], v[106:107]
	v_pk_mul_f32 v[108:109], v[108:109], v[108:109]
	v_pk_fma_f32 v[106:107], v[110:111], v[110:111], v[106:107]
	v_pk_mul_f32 v[98:99], v[98:99], v[98:99]
	v_pk_fma_f32 v[108:109], v[112:113], v[112:113], v[108:109]
	v_pk_fma_f32 v[98:99], v[102:103], v[102:103], v[98:99]
	v_add_f32_e32 v102, v106, v107
	v_add_f32_e32 v102, v108, v102
	v_add_f32_e32 v102, v109, v102
	v_pk_mul_f32 v[100:101], v[100:101], v[100:101]
	v_add_f32_e32 v98, v102, v98
	v_pk_fma_f32 v[100:101], v[104:105], v[104:105], v[100:101]
	v_add_f32_e32 v98, v99, v98
	v_add_f32_e32 v98, v100, v98
	v_add_f32_e32 v98, v101, v98
	v_mov_b32_e32 v99, v98
	s_nop 1
	v_permlane16_swap_b32_e32 v99, v98
	s_nop 1
	s_waitcnt lgkmcnt(0)
	v_add_f32_e32 v98, v98, v99
	v_mov_b32_e32 v99, v98
	s_nop 1
	v_permlane32_swap_b32_e32 v99, v98
	s_nop 1
	s_and_saveexec_b64 s[12:13], s[36:37]
	s_cbranch_execz .LBB0_574
	v_lshlrev_b64 v[100:101], 6, v[114:115]
	v_lshl_add_u64 v[100:101], s[10:11], 0, v[100:101]
	v_lshl_add_u64 v[100:101], s[52:53], 2, v[100:101]
	s_lshl_b32 s24, s68, 2
	s_waitcnt lgkmcnt(0)
	v_add_f32_e32 v98, v98, v99
	v_lshl_add_u64 v[100:101], v[100:101], 0, s[24:25]
	v_cndmask_b32_e64 v98, v98, 0, s[54:55]
	global_store_dword v[100:101], v98, off

; __device__ __forceinline__ u32x4 pack8(const f32x4 a, const f32x4 b) { u32x4 w; w.x = cvt_pk_bf16(a[0], a[1]); w.y = cvt_pk_bf16(a[2], a[3]); w.z = cvt_pk_bf16(b[0], b[1]); w.w = cvt_pk_bf16(b[2], b[3]); return w; }
;     __device__ __forceinline__ void operator()(const f32x4 (&acc)[2][2][4][2], const Unit& u, int wr, int wc, int fr, int fq) const {
;     ...
;                 for (int bj = 0; bj < 2; ++bj) { const size_t off = (size_t)row * 1024 + col0 + bj * 128; const u32x4 hv = __builtin_nontemporal_load((const u32x4*)(hin + off));
;                     f32x4 v0 = acc[ai][bj][m][0], v1 = acc[ai][bj][m][1];
;                     v0[0] += __uint_as_float(hv.x << 16); v0[1] += __uint_as_float(hv.x & 0xffff0000u); v0[2] += __uint_as_float(hv.y << 16); v0[3] += __uint_as_float(hv.y & 0xffff0000u);
;                     v1[0] += __uint_as_float(hv.z << 16); v1[1] += __uint_as_float(hv.z & 0xffff0000u); v1[2] += __uint_as_float(hv.w << 16); v1[3] += __uint_as_float(hv.w & 0xffff0000u);
; #pragma unroll
;                     for (int e = 0; e < 4; ++e) s += v0[e] * v0[e] + v1[e] * v1[e];
;                     if (!pad) *(u32x4*)(hout + off) = pack8(v0, v1); }
;                 s += __shfl_xor(s, 16); s += __shfl_xor(s, 32);
;                 if (fq == 0) ssq[(size_t)row * 16 + u.pn * 4 + wc] = pad ? 0.f : s;
.LBB0_586:
	s_or_b64 exec, exec, s[56:57]
	v_pk_mul_f32 v[90:91], v[90:91], v[90:91]
	v_pk_mul_f32 v[92:93], v[92:93], v[92:93]
	v_pk_fma_f32 v[90:91], v[94:95], v[94:95], v[90:91]
	v_pk_mul_f32 v[82:83], v[82:83], v[82:83]
	v_pk_fma_f32 v[92:93], v[96:97], v[96:97], v[92:93]
	v_pk_fma_f32 v[82:83], v[86:87], v[86:87], v[82:83]
	v_add_f32_e32 v86, v90, v91
	v_add_f32_e32 v86, v92, v86
	v_add_f32_e32 v86, v93, v86
	v_pk_mul_f32 v[84:85], v[84:85], v[84:85]
	v_add_f32_e32 v82, v86, v82
	v_pk_fma_f32 v[84:85], v[88:89], v[88:89], v[84:85]
	v_add_f32_e32 v82, v83, v82
	v_add_f32_e32 v82, v84, v82
	v_add_f32_e32 v82, v85, v82
	v_mov_b32_e32 v83, v82
	s_nop 1
	v_permlane16_swap_b32_e32 v83, v82
	s_nop 1
	s_waitcnt lgkmcnt(0)
	v_add_f32_e32 v82, v82, v83
	v_mov_b32_e32 v83, v82
	s_nop 1
	v_permlane32_swap_b32_e32 v83, v82
	s_nop 1
	s_and_saveexec_b64 s[12:13], s[36:37]
	s_cbranch_execz .LBB0_588
	v_lshlrev_b64 v[84:85], 6, v[98:99]
	v_lshl_add_u64 v[84:85], s[10:11], 0, v[84:85]
	v_lshl_add_u64 v[84:85], s[52:53], 2, v[84:85]
	s_lshl_b32 s24, s68, 2
	s_waitcnt lgkmcnt(0)
	v_add_f32_e32 v82, v82, v83
	v_lshl_add_u64 v[84:85], v[84:85], 0, s[24:25]
	v_cndmask_b32_e64 v82, v82, 0, s[54:55]
	global_store_dword v[84:85], v82, off

; __device__ __forceinline__ u32x4 pack8(const f32x4 a, const f32x4 b) { u32x4 w; w.x = cvt_pk_bf16(a[0], a[1]); w.y = cvt_pk_bf16(a[2], a[3]); w.z = cvt_pk_bf16(b[0], b[1]); w.w = cvt_pk_bf16(b[2], b[3]); return w; }
;     __device__ __forceinline__ void operator()(const f32x4 (&acc)[2][2][4][2], const Unit& u, int wr, int wc, int fr, int fq) const {
;     ...
;                 for (int bj = 0; bj < 2; ++bj) { const size_t off = (size_t)row * 1024 + col0 + bj * 128; const u32x4 hv = __builtin_nontemporal_load((const u32x4*)(hin + off));
;                     f32x4 v0 = acc[ai][bj][m][0], v1 = acc[ai][bj][m][1];
;                     v0[0] += __uint_as_float(hv.x << 16); v0[1] += __uint_as_float(hv.x & 0xffff0000u); v0[2] += __uint_as_float(hv.y << 16); v0[3] += __uint_as_float(hv.y & 0xffff0000u);
;                     v1[0] += __uint_as_float(hv.z << 16); v1[1] += __uint_as_float(hv.z & 0xffff0000u); v1[2] += __uint_as_float(hv.w << 16); v1[3] += __uint_as_float(hv.w & 0xffff0000u);
; #pragma unroll
;                     for (int e = 0; e < 4; ++e) s += v0[e] * v0[e] + v1[e] * v1[e];
;                     if (!pad) *(u32x4*)(hout + off) = pack8(v0, v1); }
;                 s += __shfl_xor(s, 16); s += __shfl_xor(s, 32);
;                 if (fq == 0) ssq[(size_t)row * 16 + u.pn * 4 + wc] = pad ? 0.f : s;
.LBB0_600:
	s_or_b64 exec, exec, s[56:57]
	v_pk_mul_f32 v[74:75], v[74:75], v[74:75]
	v_pk_mul_f32 v[76:77], v[76:77], v[76:77]
	v_pk_fma_f32 v[74:75], v[78:79], v[78:79], v[74:75]
	v_pk_mul_f32 v[66:67], v[66:67], v[66:67]
	v_pk_fma_f32 v[76:77], v[80:81], v[80:81], v[76:77]
	v_pk_fma_f32 v[66:67], v[70:71], v[70:71], v[66:67]
	v_add_f32_e32 v70, v74, v75
	v_add_f32_e32 v70, v76, v70
	v_add_f32_e32 v70, v77, v70
	v_pk_mul_f32 v[68:69], v[68:69], v[68:69]
	v_add_f32_e32 v66, v70, v66
	v_pk_fma_f32 v[68:69], v[72:73], v[72:73], v[68:69]
	v_add_f32_e32 v66, v67, v66
	v_add_f32_e32 v66, v68, v66
	v_add_f32_e32 v66, v69, v66
	v_mov_b32_e32 v67, v66
	s_nop 1
	v_permlane16_swap_b32_e32 v67, v66
	s_nop 1
	s_waitcnt lgkmcnt(0)
	v_add_f32_e32 v66, v66, v67
	v_mov_b32_e32 v67, v66
	s_nop 1
	v_permlane32_swap_b32_e32 v67, v66
	s_nop 1
	s_and_saveexec_b64 s[12:13], s[36:37]
	s_cbranch_execz .LBB0_602
	v_lshlrev_b64 v[68:69], 6, v[82:83]
	v_lshl_add_u64 v[68:69], s[10:11], 0, v[68:69]
	v_lshl_add_u64 v[68:69], s[52:53], 2, v[68:69]
	s_lshl_b32 s24, s68, 2
	s_waitcnt lgkmcnt(0)
	v_add_f32_e32 v66, v66, v67
	v_lshl_add_u64 v[68:69], v[68:69], 0, s[24:25]
	v_cndmask_b32_e64 v66, v66, 0, s[54:55]
	global_store_dword v[68:69], v66, off

; __device__ __forceinline__ u32x4 pack8(const f32x4 a, const f32x4 b) { u32x4 w; w.x = cvt_pk_bf16(a[0], a[1]); w.y = cvt_pk_bf16(a[2], a[3]); w.z = cvt_pk_bf16(b[0], b[1]); w.w = cvt_pk_bf16(b[2], b[3]); return w; }
;     __device__ __forceinline__ void operator()(const f32x4 (&acc)[2][2][4][2], const Unit& u, int wr, int wc, int fr, int fq) const {
;     ...
;                 for (int bj = 0; bj < 2; ++bj) { const size_t off = (size_t)row * 1024 + col0 + bj * 128; const u32x4 hv = __builtin_nontemporal_load((const u32x4*)(hin + off));
;                     f32x4 v0 = acc[ai][bj][m][0], v1 = acc[ai][bj][m][1];
;                     v0[0] += __uint_as_float(hv.x << 16); v0[1] += __uint_as_float(hv.x & 0xffff0000u); v0[2] += __uint_as_float(hv.y << 16); v0[3] += __uint_as_float(hv.y & 0xffff0000u);
;                     v1[0] += __uint_as_float(hv.z << 16); v1[1] += __uint_as_float(hv.z & 0xffff0000u); v1[2] += __uint_as_float(hv.w << 16); v1[3] += __uint_as_float(hv.w & 0xffff0000u);
; #pragma unroll
;                     for (int e = 0; e < 4; ++e) s += v0[e] * v0[e] + v1[e] * v1[e];
;                     if (!pad) *(u32x4*)(hout + off) = pack8(v0, v1); }
;                 s += __shfl_xor(s, 16); s += __shfl_xor(s, 32);
;                 if (fq == 0) ssq[(size_t)row * 16 + u.pn * 4 + wc] = pad ? 0.f : s;
.LBB0_614:
	s_or_b64 exec, exec, s[56:57]
	v_pk_mul_f32 v[58:59], v[58:59], v[58:59]
	v_pk_mul_f32 v[60:61], v[60:61], v[60:61]
	v_pk_fma_f32 v[58:59], v[62:63], v[62:63], v[58:59]
	v_pk_mul_f32 v[50:51], v[50:51], v[50:51]
	v_pk_fma_f32 v[60:61], v[64:65], v[64:65], v[60:61]
	v_pk_fma_f32 v[50:51], v[54:55], v[54:55], v[50:51]
	v_add_f32_e32 v54, v58, v59
	v_add_f32_e32 v54, v60, v54
	v_add_f32_e32 v54, v61, v54
	v_pk_mul_f32 v[52:53], v[52:53], v[52:53]
	v_add_f32_e32 v50, v54, v50
	v_pk_fma_f32 v[52:53], v[56:57], v[56:57], v[52:53]
	v_add_f32_e32 v50, v51, v50
	v_add_f32_e32 v50, v52, v50
	v_add_f32_e32 v50, v53, v50
	v_mov_b32_e32 v51, v50
	s_nop 1
	v_permlane16_swap_b32_e32 v51, v50
	s_nop 1
	s_waitcnt lgkmcnt(0)
	v_add_f32_e32 v50, v50, v51
	v_mov_b32_e32 v51, v50
	s_nop 1
	v_permlane32_swap_b32_e32 v51, v50
	s_nop 1
	s_and_saveexec_b64 s[12:13], s[36:37]
	s_cbranch_execz .LBB0_616
	v_lshlrev_b64 v[52:53], 6, v[66:67]
	v_lshl_add_u64 v[52:53], s[10:11], 0, v[52:53]
	v_lshl_add_u64 v[52:53], s[52:53], 2, v[52:53]
	s_lshl_b32 s24, s68, 2
	s_waitcnt lgkmcnt(0)
	v_add_f32_e32 v50, v50, v51
	v_lshl_add_u64 v[52:53], v[52:53], 0, s[24:25]
	v_cndmask_b32_e64 v50, v50, 0, s[54:55]
	global_store_dword v[52:53], v50, off

; __device__ __forceinline__ u32x4 pack8(const f32x4 a, const f32x4 b) { u32x4 w; w.x = cvt_pk_bf16(a[0], a[1]); w.y = cvt_pk_bf16(a[2], a[3]); w.z = cvt_pk_bf16(b[0], b[1]); w.w = cvt_pk_bf16(b[2], b[3]); return w; }
;     __device__ __forceinline__ void operator()(const f32x4 (&acc)[2][2][4][2], const Unit& u, int wr, int wc, int fr, int fq) const {
;     ...
;                 for (int bj = 0; bj < 2; ++bj) { const size_t off = (size_t)row * 1024 + col0 + bj * 128; const u32x4 hv = __builtin_nontemporal_load((const u32x4*)(hin + off));
;                     f32x4 v0 = acc[ai][bj][m][0], v1 = acc[ai][bj][m][1];
;                     v0[0] += __uint_as_float(hv.x << 16); v0[1] += __uint_as_float(hv.x & 0xffff0000u); v0[2] += __uint_as_float(hv.y << 16); v0[3] += __uint_as_float(hv.y & 0xffff0000u);
;                     v1[0] += __uint_as_float(hv.z << 16); v1[1] += __uint_as_float(hv.z & 0xffff0000u); v1[2] += __uint_as_float(hv.w << 16); v1[3] += __uint_as_float(hv.w & 0xffff0000u);
; #pragma unroll
;                     for (int e = 0; e < 4; ++e) s += v0[e] * v0[e] + v1[e] * v1[e];
;                     if (!pad) *(u32x4*)(hout + off) = pack8(v0, v1); }
;                 s += __shfl_xor(s, 16); s += __shfl_xor(s, 32);
;                 if (fq == 0) ssq[(size_t)row * 16 + u.pn * 4 + wc] = pad ? 0.f : s;
.LBB0_628:
	s_or_b64 exec, exec, s[56:57]
	v_pk_mul_f32 v[42:43], v[42:43], v[42:43]
	v_pk_mul_f32 v[44:45], v[44:45], v[44:45]
	v_pk_fma_f32 v[42:43], v[46:47], v[46:47], v[42:43]
	v_pk_mul_f32 v[34:35], v[34:35], v[34:35]
	v_pk_fma_f32 v[44:45], v[48:49], v[48:49], v[44:45]
	v_pk_fma_f32 v[34:35], v[38:39], v[38:39], v[34:35]
	v_add_f32_e32 v38, v42, v43
	v_add_f32_e32 v38, v44, v38
	v_add_f32_e32 v38, v45, v38
	v_pk_mul_f32 v[36:37], v[36:37], v[36:37]
	v_add_f32_e32 v34, v38, v34
	v_pk_fma_f32 v[36:37], v[40:41], v[40:41], v[36:37]
	v_add_f32_e32 v34, v35, v34
	v_add_f32_e32 v34, v36, v34
	v_add_f32_e32 v34, v37, v34
	v_mov_b32_e32 v35, v34
	s_nop 1
	v_permlane16_swap_b32_e32 v35, v34
	s_nop 1
	s_waitcnt lgkmcnt(0)
	v_add_f32_e32 v34, v34, v35
	v_mov_b32_e32 v35, v34
	s_nop 1
	v_permlane32_swap_b32_e32 v35, v34
	s_nop 1
	s_and_saveexec_b64 s[12:13], s[36:37]
	s_cbranch_execz .LBB0_630
	v_lshlrev_b64 v[36:37], 6, v[50:51]
	v_lshl_add_u64 v[36:37], s[10:11], 0, v[36:37]
	v_lshl_add_u64 v[36:37], s[52:53], 2, v[36:37]
	s_lshl_b32 s24, s68, 2
	s_waitcnt lgkmcnt(0)
	v_add_f32_e32 v34, v34, v35
	v_lshl_add_u64 v[36:37], v[36:37], 0, s[24:25]
	v_cndmask_b32_e64 v34, v34, 0, s[54:55]
	global_store_dword v[36:37], v34, off

; __device__ __forceinline__ u32x4 pack8(const f32x4 a, const f32x4 b) { u32x4 w; w.x = cvt_pk_bf16(a[0], a[1]); w.y = cvt_pk_bf16(a[2], a[3]); w.z = cvt_pk_bf16(b[0], b[1]); w.w = cvt_pk_bf16(b[2], b[3]); return w; }
;     __device__ __forceinline__ void operator()(const f32x4 (&acc)[2][2][4][2], const Unit& u, int wr, int wc, int fr, int fq) const {
;     ...
;                 for (int bj = 0; bj < 2; ++bj) { const size_t off = (size_t)row * 1024 + col0 + bj * 128; const u32x4 hv = __builtin_nontemporal_load((const u32x4*)(hin + off));
;                     f32x4 v0 = acc[ai][bj][m][0], v1 = acc[ai][bj][m][1];
;                     v0[0] += __uint_as_float(hv.x << 16); v0[1] += __uint_as_float(hv.x & 0xffff0000u); v0[2] += __uint_as_float(hv.y << 16); v0[3] += __uint_as_float(hv.y & 0xffff0000u);
;                     v1[0] += __uint_as_float(hv.z << 16); v1[1] += __uint_as_float(hv.z & 0xffff0000u); v1[2] += __uint_as_float(hv.w << 16); v1[3] += __uint_as_float(hv.w & 0xffff0000u);
; #pragma unroll
;                     for (int e = 0; e < 4; ++e) s += v0[e] * v0[e] + v1[e] * v1[e];
;                     if (!pad) *(u32x4*)(hout + off) = pack8(v0, v1); }
;                 s += __shfl_xor(s, 16); s += __shfl_xor(s, 32);
;                 if (fq == 0) ssq[(size_t)row * 16 + u.pn * 4 + wc] = pad ? 0.f : s;
.LBB0_642:
	s_or_b64 exec, exec, s[56:57]
	v_pk_mul_f32 v[26:27], v[26:27], v[26:27]
	v_pk_mul_f32 v[28:29], v[28:29], v[28:29]
	v_pk_fma_f32 v[26:27], v[30:31], v[30:31], v[26:27]
	v_pk_mul_f32 v[18:19], v[18:19], v[18:19]
	v_pk_fma_f32 v[28:29], v[32:33], v[32:33], v[28:29]
	v_pk_fma_f32 v[18:19], v[22:23], v[22:23], v[18:19]
	v_add_f32_e32 v22, v26, v27
	v_add_f32_e32 v22, v28, v22
	v_add_f32_e32 v22, v29, v22
	v_pk_mul_f32 v[20:21], v[20:21], v[20:21]
	v_add_f32_e32 v18, v22, v18
	v_pk_fma_f32 v[20:21], v[24:25], v[24:25], v[20:21]
	v_add_f32_e32 v18, v19, v18
	v_add_f32_e32 v18, v20, v18
	v_add_f32_e32 v18, v21, v18
	v_mov_b32_e32 v19, v18
	s_nop 1
	v_permlane16_swap_b32_e32 v19, v18
	s_nop 1
	s_waitcnt lgkmcnt(0)
	v_add_f32_e32 v18, v18, v19
	v_mov_b32_e32 v19, v18
	s_nop 1
	v_permlane32_swap_b32_e32 v19, v18
	s_nop 1
	s_and_saveexec_b64 s[12:13], s[36:37]
	s_cbranch_execz .LBB0_644
	v_lshlrev_b64 v[20:21], 6, v[34:35]
	v_lshl_add_u64 v[20:21], s[10:11], 0, v[20:21]
	v_lshl_add_u64 v[20:21], s[52:53], 2, v[20:21]
	s_lshl_b32 s24, s68, 2
	s_waitcnt lgkmcnt(0)
	v_add_f32_e32 v18, v18, v19
	v_lshl_add_u64 v[20:21], v[20:21], 0, s[24:25]
	v_cndmask_b32_e64 v18, v18, 0, s[54:55]
	global_store_dword v[20:21], v18, off

; __device__ __forceinline__ u32x4 pack8(const f32x4 a, const f32x4 b) { u32x4 w; w.x = cvt_pk_bf16(a[0], a[1]); w.y = cvt_pk_bf16(a[2], a[3]); w.z = cvt_pk_bf16(b[0], b[1]); w.w = cvt_pk_bf16(b[2], b[3]); return w; }
;     __device__ __forceinline__ void operator()(const f32x4 (&acc)[2][2][4][2], const Unit& u, int wr, int wc, int fr, int fq) const {
;     ...
;                 for (int bj = 0; bj < 2; ++bj) { const size_t off = (size_t)row * 1024 + col0 + bj * 128; const u32x4 hv = __builtin_nontemporal_load((const u32x4*)(hin + off));
;                     f32x4 v0 = acc[ai][bj][m][0], v1 = acc[ai][bj][m][1];
;                     v0[0] += __uint_as_float(hv.x << 16); v0[1] += __uint_as_float(hv.x & 0xffff0000u); v0[2] += __uint_as_float(hv.y << 16); v0[3] += __uint_as_float(hv.y & 0xffff0000u);
;                     v1[0] += __uint_as_float(hv.z << 16); v1[1] += __uint_as_float(hv.z & 0xffff0000u); v1[2] += __uint_as_float(hv.w << 16); v1[3] += __uint_as_float(hv.w & 0xffff0000u);
; #pragma unroll
;                     for (int e = 0; e < 4; ++e) s += v0[e] * v0[e] + v1[e] * v1[e];
;                     if (!pad) *(u32x4*)(hout + off) = pack8(v0, v1); }
;                 s += __shfl_xor(s, 16); s += __shfl_xor(s, 32);
;                 if (fq == 0) ssq[(size_t)row * 16 + u.pn * 4 + wc] = pad ? 0.f : s;
.LBB0_656:
	s_or_b64 exec, exec, s[56:57]
	v_pk_mul_f32 v[10:11], v[10:11], v[10:11]
	v_pk_mul_f32 v[12:13], v[12:13], v[12:13]
	v_pk_fma_f32 v[10:11], v[14:15], v[14:15], v[10:11]
	v_pk_mul_f32 v[2:3], v[2:3], v[2:3]
	v_pk_fma_f32 v[12:13], v[16:17], v[16:17], v[12:13]
	v_pk_fma_f32 v[2:3], v[6:7], v[6:7], v[2:3]
	v_add_f32_e32 v6, v10, v11
	v_add_f32_e32 v6, v12, v6
	v_add_f32_e32 v6, v13, v6
	v_pk_mul_f32 v[4:5], v[4:5], v[4:5]
	v_add_f32_e32 v2, v6, v2
	v_pk_fma_f32 v[4:5], v[8:9], v[8:9], v[4:5]
	v_add_f32_e32 v2, v3, v2
	v_add_f32_e32 v2, v4, v2
	v_add_f32_e32 v2, v5, v2
	v_mov_b32_e32 v3, v2
	s_nop 1
	v_permlane16_swap_b32_e32 v3, v2
	s_nop 1
	s_waitcnt lgkmcnt(0)
	v_add_f32_e32 v2, v2, v3
	v_mov_b32_e32 v3, v2
	s_nop 1
	v_permlane32_swap_b32_e32 v3, v2
	s_nop 1
	s_and_saveexec_b64 s[12:13], s[36:37]
	s_cbranch_execz .LBB0_658
	v_lshlrev_b64 v[4:5], 6, v[18:19]
	v_lshl_add_u64 v[4:5], s[10:11], 0, v[4:5]
	v_lshl_add_u64 v[4:5], s[52:53], 2, v[4:5]
	s_lshl_b32 s24, s68, 2
	s_waitcnt lgkmcnt(0)
	v_add_f32_e32 v2, v2, v3
	v_lshl_add_u64 v[4:5], v[4:5], 0, s[24:25]
	v_cndmask_b32_e64 v2, v2, 0, s[54:55]
	global_store_dword v[4:5], v2, off
